# P4 small-tile GEMM K loop hand-written: K split over waves, operands straight from L2, LDS only for the final reduction
# baseline (speedup 1.0000x reference)
; #define LAS __attribute__((address_space(3)))
; #define SG_LOAD(kc, sg) do { _Pragma("unroll") for (int i_ = 0; i_ < 4; ++i_) { const int idx_ = tid + 512 * i_; \
;             ra[sg][i_] = *(const u32x4*)(A + (size_t)(row0 + (idx_ >> 5)) * ld + (kc) * 256 + (idx_ & 31) * 8); if (NC == 64 || i_ < 2) rb[sg][i_] = *(const u32x4*)(Bt + (size_t)(col0 + (idx_ >> 5)) * ld + (kc) * 256 + (idx_ & 31) * 8); } } while (0)
; template <int NC, class Epi>
; __device__ __forceinline__ void small_gemm_phase(LAS unsigned char* lds, const bf16_t* A, const bf16_t* Bt, int K, int ld, int ncolt  , const Epi& E, int first, int nblk, int bid, int tid) {
;     ...
;     for (int u = ub; u < 8 * ncolt; u += nblk) {
;         const int rt = u & 7, ct = u >> 3;
;         const int row0 = NPT + 64 * rt, col0 = NC * ct;
;         u32x4 ra[2][4], rb[2][4];
;     ...
;         SG_LOAD(0, 0); SG_LOAD(1, 1);
;         f32x4 acc0 = {0.f, 0.f, 0.f, 0.f}, acc1 = {0.f, 0.f, 0.f, 0.f};
;         const LAS unsigned char* apl = lds + (16 * mt + fr) * SG_STRIDE + 16 * fq;
;         const LAS unsigned char* bpl = lds + SG_BOFF + ((NC / 2) * nh + fr) * SG_STRIDE + 16 * fq;
; #pragma unroll 1
;         for (int kc = 0; kc < nch; kc += 2) { SG_STEP(kc, 0); SG_STEP(kc + 1, 1); }
.LBB0_812:
	s_lshl_b32 s18, s3, 6
	s_and_b32 s13, s18, 0x1c0
	s_bitset1_b32 s13, 14
	s_lshl_b32 s18, s3, 2
	s_and_b32 s12, s18, 0x7fffffe0
	s_lshl_b32 s18, s13, 11
	s_add_u32 s10, s58, s18
	s_addc_u32 s11, s59, 0
	s_add_u32 s10, s10, 0x8f00000
	s_addc_u32 s11, s11, 0
	s_lshl_b32 s18, s12, 11
	s_add_u32 s14, s58, s18
	s_addc_u32 s15, s59, 0
	s_add_u32 s14, s14, 0xb00000
	s_addc_u32 s15, s15, 0
	v_and_b32_e32 v241, 15, v192
	v_bfe_u32 v240, v192, 4, 2
	v_lshrrev_b32_e32 v239, 6, v192
	v_lshlrev_b32_e32 v238, 11, v241
	v_lshl_add_u32 v238, v240, 4, v238
	v_lshl_add_u32 v238, v239, 8, v238
	v_mov_b32_e32 v235, v238
	v_add_u32_e32 v234, 0x8000, v238
	v_add_u32_e32 v233, 0x10000, v238
	v_add_u32_e32 v232, 0x18000, v238
	v_mov_b32_e32 v231, v238
	v_add_u32_e32 v230, 0x8000, v238
	v_mov_b32_e32 v0, 0
	v_mov_b32_e32 v1, 0
	v_mov_b32_e32 v2, 0
	v_mov_b32_e32 v3, 0
	v_mov_b32_e32 v4, 0
	v_mov_b32_e32 v5, 0
	v_mov_b32_e32 v6, 0
	v_mov_b32_e32 v7, 0
	v_mov_b32_e32 v8, 0
	v_mov_b32_e32 v9, 0
	v_mov_b32_e32 v10, 0
	v_mov_b32_e32 v11, 0
	v_mov_b32_e32 v12, 0
	v_mov_b32_e32 v13, 0
	v_mov_b32_e32 v14, 0
	v_mov_b32_e32 v15, 0
	v_mov_b32_e32 v16, 0
	v_mov_b32_e32 v17, 0
	v_mov_b32_e32 v18, 0
	v_mov_b32_e32 v19, 0
	v_mov_b32_e32 v20, 0
	v_mov_b32_e32 v21, 0
	v_mov_b32_e32 v22, 0
	v_mov_b32_e32 v23, 0
	v_mov_b32_e32 v24, 0
	v_mov_b32_e32 v25, 0
	v_mov_b32_e32 v26, 0
	v_mov_b32_e32 v27, 0
	v_mov_b32_e32 v28, 0
	v_mov_b32_e32 v29, 0
	v_mov_b32_e32 v30, 0
	v_mov_b32_e32 v31, 0
	global_load_dwordx4 v[32:35], v235, s[10:11] offset:0
	global_load_dwordx4 v[36:39], v234, s[10:11] offset:0
	global_load_dwordx4 v[40:43], v233, s[10:11] offset:0
	global_load_dwordx4 v[44:47], v232, s[10:11] offset:0
	global_load_dwordx4 v[58:61], v231, s[14:15] offset:0
	global_load_dwordx4 v[62:65], v230, s[14:15] offset:0
	global_load_dwordx4 v[66:69], v235, s[10:11] offset:64
	global_load_dwordx4 v[100:103], v234, s[10:11] offset:64
	global_load_dwordx4 v[104:107], v233, s[10:11] offset:64
	global_load_dwordx4 v[108:111], v232, s[10:11] offset:64
	global_load_dwordx4 v[112:115], v231, s[14:15] offset:64
	global_load_dwordx4 v[116:119], v230, s[14:15] offset:64
	global_load_dwordx4 v[120:123], v235, s[10:11] offset:128
	global_load_dwordx4 v[124:127], v234, s[10:11] offset:128
	global_load_dwordx4 v[128:131], v233, s[10:11] offset:128
	global_load_dwordx4 v[132:135], v232, s[10:11] offset:128
	global_load_dwordx4 v[136:139], v231, s[14:15] offset:128
	global_load_dwordx4 v[140:143], v230, s[14:15] offset:128
	global_load_dwordx4 v[144:147], v235, s[10:11] offset:192
	global_load_dwordx4 v[148:151], v234, s[10:11] offset:192
	global_load_dwordx4 v[152:155], v233, s[10:11] offset:192
	global_load_dwordx4 v[156:159], v232, s[10:11] offset:192
	global_load_dwordx4 v[160:163], v231, s[14:15] offset:192
	global_load_dwordx4 v[164:167], v230, s[14:15] offset:192
	s_waitcnt vmcnt(18)
	v_mfma_f32_16x16x32_bf16 v[0:3], v[58:61], v[32:35], v[0:3]
	v_mfma_f32_16x16x32_bf16 v[4:7], v[62:65], v[32:35], v[4:7]
	v_mfma_f32_16x16x32_bf16 v[8:11], v[58:61], v[36:39], v[8:11]
	v_mfma_f32_16x16x32_bf16 v[12:15], v[62:65], v[36:39], v[12:15]
	v_mfma_f32_16x16x32_bf16 v[16:19], v[58:61], v[40:43], v[16:19]
	v_mfma_f32_16x16x32_bf16 v[20:23], v[62:65], v[40:43], v[20:23]
	v_mfma_f32_16x16x32_bf16 v[24:27], v[58:61], v[44:47], v[24:27]
	v_mfma_f32_16x16x32_bf16 v[28:31], v[62:65], v[44:47], v[28:31]
	s_waitcnt vmcnt(12)
	v_mfma_f32_16x16x32_bf16 v[0:3], v[112:115], v[66:69], v[0:3]
	v_mfma_f32_16x16x32_bf16 v[4:7], v[116:119], v[66:69], v[4:7]
	v_mfma_f32_16x16x32_bf16 v[8:11], v[112:115], v[100:103], v[8:11]
	v_mfma_f32_16x16x32_bf16 v[12:15], v[116:119], v[100:103], v[12:15]
	v_mfma_f32_16x16x32_bf16 v[16:19], v[112:115], v[104:107], v[16:19]
	v_mfma_f32_16x16x32_bf16 v[20:23], v[116:119], v[104:107], v[20:23]
	v_mfma_f32_16x16x32_bf16 v[24:27], v[112:115], v[108:111], v[24:27]
	v_mfma_f32_16x16x32_bf16 v[28:31], v[116:119], v[108:111], v[28:31]
	s_waitcnt vmcnt(6)
	v_mfma_f32_16x16x32_bf16 v[0:3], v[136:139], v[120:123], v[0:3]
	v_mfma_f32_16x16x32_bf16 v[4:7], v[140:143], v[120:123], v[4:7]
	v_mfma_f32_16x16x32_bf16 v[8:11], v[136:139], v[124:127], v[8:11]
	v_mfma_f32_16x16x32_bf16 v[12:15], v[140:143], v[124:127], v[12:15]
	v_mfma_f32_16x16x32_bf16 v[16:19], v[136:139], v[128:131], v[16:19]
	v_mfma_f32_16x16x32_bf16 v[20:23], v[140:143], v[128:131], v[20:23]
	v_mfma_f32_16x16x32_bf16 v[24:27], v[136:139], v[132:135], v[24:27]
	v_mfma_f32_16x16x32_bf16 v[28:31], v[140:143], v[132:135], v[28:31]
	s_waitcnt vmcnt(0)
	v_mfma_f32_16x16x32_bf16 v[0:3], v[160:163], v[144:147], v[0:3]
	v_mfma_f32_16x16x32_bf16 v[4:7], v[164:167], v[144:147], v[4:7]
	v_mfma_f32_16x16x32_bf16 v[8:11], v[160:163], v[148:151], v[8:11]
	v_mfma_f32_16x16x32_bf16 v[12:15], v[164:167], v[148:151], v[12:15]
	v_mfma_f32_16x16x32_bf16 v[16:19], v[160:163], v[152:155], v[16:19]
	v_mfma_f32_16x16x32_bf16 v[20:23], v[164:167], v[152:155], v[20:23]
	v_mfma_f32_16x16x32_bf16 v[24:27], v[160:163], v[156:159], v[24:27]
	v_mfma_f32_16x16x32_bf16 v[28:31], v[164:167], v[156:159], v[28:31]
	v_lshlrev_b32_e32 v237, 4, v192
	v_mul_u32_u24_e32 v236, 0x1c00, v239
	v_add_u32_e32 v236, v237, v236
	s_nop 15
	s_nop 15
	ds_write_b128 v236, v[0:3] offset:0
	ds_write_b128 v236, v[4:7] offset:1024
	ds_write_b128 v236, v[8:11] offset:2048
	ds_write_b128 v236, v[12:15] offset:3072
	ds_write_b128 v236, v[16:19] offset:4096
	ds_write_b128 v236, v[20:23] offset:5120
	ds_write_b128 v236, v[24:27] offset:6144
	ds_write_b128 v236, v[28:31] offset:7168
	s_waitcnt lgkmcnt(0)
	s_barrier
	ds_read_b128 v[32:35], v237 offset:0
	ds_read_b128 v[36:39], v237 offset:8192
	ds_read_b128 v[40:43], v237 offset:16384
	ds_read_b128 v[44:47], v237 offset:24576
	ds_read_b128 v[58:61], v237 offset:32768
	ds_read_b128 v[62:65], v237 offset:40960
	ds_read_b128 v[66:69], v237 offset:49152
	ds_read_b128 v[100:103], v237 offset:57344
	s_waitcnt lgkmcnt(6)
	v_pk_add_f32 v[48:49], v[32:33], v[36:37]
	v_pk_add_f32 v[50:51], v[34:35], v[38:39]
	s_waitcnt lgkmcnt(5)
	v_pk_add_f32 v[48:49], v[48:49], v[40:41]
	v_pk_add_f32 v[50:51], v[50:51], v[42:43]
	s_waitcnt lgkmcnt(4)
	v_pk_add_f32 v[48:49], v[48:49], v[44:45]
	v_pk_add_f32 v[50:51], v[50:51], v[46:47]
	s_waitcnt lgkmcnt(3)
	v_pk_add_f32 v[48:49], v[48:49], v[58:59]
	v_pk_add_f32 v[50:51], v[50:51], v[60:61]
	s_waitcnt lgkmcnt(2)
	v_pk_add_f32 v[48:49], v[48:49], v[62:63]
	v_pk_add_f32 v[50:51], v[50:51], v[64:65]
	s_waitcnt lgkmcnt(1)
	v_pk_add_f32 v[48:49], v[48:49], v[66:67]
	v_pk_add_f32 v[50:51], v[50:51], v[68:69]
	s_waitcnt lgkmcnt(0)
	v_pk_add_f32 v[48:49], v[48:49], v[100:101]
	v_pk_add_f32 v[50:51], v[50:51], v[102:103]
	s_barrier
	s_branch .LBB0_811
